# attention ring loops: LDS-DMA m0 targets computed with SALU from a per-wave base instead of VALU + v_readfirstlane each step
# speedup vs baseline: 1.0051x; 1.0012x over previous
.LBB0_1073:
	s_lshl_b32 s0, s93, 5
	s_bitcmp0_b32 s93, 0
	v_readlane_b32 s1, v252, 49
	v_readlane_b32 s2, v253, 2
	s_cselect_b32 s1, s1, s2
	s_add_i32 s0, s1, s0
	s_ashr_i32 s0, s0, 1
	v_mov_b32 v37, v178
	s_sub_i32 s68, 63, s0
	v_ashrrev_i32_e32 v225, 6, v37
	v_lshlrev_b32_e32 v207, 3, v225
	v_bfe_u32 v208, v37, 2, 3
	s_lshl_b32 s33, s68, 6
	v_or_b32_e32 v226, v207, v208
	v_add_u32_e32 v184, s33, v226
	v_ashrrev_i32_e32 v185, 31, v184
	s_and_b32 s2, s1, 1
	v_and_b32_e32 v36, 3, v37
	v_lshl_add_u64 v[34:35], v[184:185], 0, s[70:71]
	s_nop 0
	v_lshlrev_b64 v[2:3], 10, v[34:35]
	v_readlane_b32 s18, v252, 5
	v_readlane_b32 s19, v252, 6
	v_lshl_or_b32 v42, s2, 2, v36
	v_bfe_u32 v199, v37, 5, 1
	v_lshl_add_u64 v[2:3], s[18:19], 0, v[2:3]
	v_lshlrev_b32_e32 v0, 7, v42
	v_lshl_add_u64 v[2:3], v[2:3], 0, v[0:1]
	v_lshlrev_b32_e32 v0, 4, v199
	v_lshl_add_u64 v[2:3], v[2:3], 0, v[0:1]
	s_movk_i32 s3, 0x60
	s_mov_b32 s74, s0
	global_load_dwordx4 v[162:165], v[2:3], off
	global_load_dwordx4 v[166:169], v[2:3], off offset:32
	global_load_dwordx4 v[170:173], v[2:3], off offset:64
	global_load_dwordx4 v[174:177], v[2:3], off offset:96
	v_mad_u64_u32 v[2:3], s[0:1], v34, s3, v[180:181]
	s_nop 7
	s_nop 4
	v_mad_i32_i24 v3, v35, s3, v3
	s_lshl_b32 s72, s2, 4
	v_lshl_add_u64 v[2:3], v[2:3], 0, s[72:73]
	v_lshlrev_b32_e32 v0, 2, v36
	s_nop 0
	s_or_b32 s20, s2, s65
	v_lshl_add_u64 v[2:3], v[2:3], 0, v[0:1]
	s_nop 1
	v_readlane_b32 s14, v252, 17
	v_readlane_b32 s15, v252, 18
	global_load_dword v0, v[2:3], off
	global_load_dword v223, v[2:3], off offset:32
	global_load_dword v185, v[2:3], off offset:64
	s_lshl_b32 s2, s20, 15
	s_mov_b64 s[10:11], s[14:15]
	v_lshrrev_b32_e32 v3, 4, v37
	s_nop 1
	v_readlane_b32 s16, v252, 19
	v_readlane_b32 s17, v252, 20
	s_add_u32 s0, s10, s2
	v_lshlrev_b32_e32 v38, 3, v37
	v_xor_b32_e32 v3, v3, v37
	v_readlane_b32 s18, v252, 21
	v_readlane_b32 s19, v252, 22
	s_mov_b64 s[12:13], s[16:17]
	s_addc_u32 s1, s11, 0
	v_and_b32_e32 v2, 0xffffffc0, v38
	v_lshlrev_b32_e32 v3, 3, v3
	s_add_u32 s2, s12, s2
	v_and_or_b32 v186, v3, 56, v2
	v_lshlrev_b32_e32 v224, 4, v37
	s_mov_b32 s4, 0x1ffffffc
	s_addc_u32 s3, s13, 0
	s_ashr_i32 s72, s68, 4
	v_and_b32_e32 v2, 0xfc0, v224
	v_and_or_b32 v3, v225, s4, v36
	v_ashrrev_i32_e32 v187, 31, v186
	v_lshl_add_u32 v188, v3, 3, v2
	v_lshl_add_u64 v[2:3], v[186:187], 1, s[0:1]
	s_min_i32 s0, s72, 0
	v_ashrrev_i32_e32 v189, 31, v188
	s_ashr_i32 s1, s0, 31
	v_add_u32_e32 v200, 0, v224
	s_nop 0
	v_readfirstlane_b32 s99, v200
	v_lshl_add_u64 v[4:5], v[188:189], 1, s[2:3]
	s_lshl_b64 s[0:1], s[0:1], 13
	v_readfirstlane_b32 s2, v200
	v_lshl_add_u64 v[6:7], v[2:3], 0, s[0:1]
	s_mov_b32 m0, s2
	v_add_u32_e32 v213, 0x2000, v200
	global_load_lds_dwordx4 v[6:7], off
	v_lshl_add_u64 v[6:7], v[4:5], 0, s[0:1]
	v_readfirstlane_b32 s0, v213
	s_mov_b32 m0, s0
	s_min_i32 s0, s72, 1
	s_ashr_i32 s1, s0, 31
	v_add_u32_e32 v214, 0x4000, v200
	s_lshl_b64 s[0:1], s[0:1], 13
	v_readfirstlane_b32 s2, v214
	global_load_lds_dwordx4 v[6:7], off
	v_lshl_add_u64 v[6:7], v[2:3], 0, s[0:1]
	s_mov_b32 m0, s2
	v_add_u32_e32 v215, 0x6000, v200
	global_load_lds_dwordx4 v[6:7], off
	v_lshl_add_u64 v[6:7], v[4:5], 0, s[0:1]
	v_readfirstlane_b32 s0, v215
	s_mov_b32 m0, s0
	s_min_i32 s0, s72, 2
	s_ashr_i32 s1, s0, 31
	v_add_u32_e32 v216, 0x8000, v200
	s_lshl_b64 s[0:1], s[0:1], 13
	v_readfirstlane_b32 s2, v216
	global_load_lds_dwordx4 v[6:7], off
	v_lshl_add_u64 v[6:7], v[2:3], 0, s[0:1]
	s_mov_b32 m0, s2
	v_add_u32_e32 v217, 0xa000, v200
	global_load_lds_dwordx4 v[6:7], off
	v_lshl_add_u64 v[6:7], v[4:5], 0, s[0:1]
	v_readfirstlane_b32 s0, v217
	s_mov_b32 m0, s0
	s_min_i32 s0, s72, 3
	s_ashr_i32 s1, s0, 31
	v_add_u32_e32 v218, 0xc000, v200
	s_lshl_b64 s[0:1], s[0:1], 13
	v_readfirstlane_b32 s2, v218
	global_load_lds_dwordx4 v[6:7], off
	v_lshl_add_u64 v[2:3], v[2:3], 0, s[0:1]
	s_mov_b32 m0, s2
	v_add_u32_e32 v221, 0xe000, v200
	global_load_lds_dwordx4 v[2:3], off
	v_lshl_add_u64 v[2:3], v[4:5], 0, s[0:1]
	v_readfirstlane_b32 s0, v221
	s_mov_b32 m0, s0
	s_sub_i32 s0, s33, 31
	global_load_lds_dwordx4 v[2:3], off
	v_subrev_u32_e32 v2, 31, v184
	v_ashrrev_i32_e32 v40, 4, v2
	v_lshrrev_b32_e32 v2, 5, v37
	v_bfe_u32 v3, v37, 1, 3
	v_bitop3_b32 v2, v2, v3, 1 bitop3:0x6c
	v_lshlrev_b32_e32 v201, 4, v2
	v_bitop3_b32 v2, v199, v3, 2 bitop3:0x36
	v_lshlrev_b32_e32 v202, 4, v2
	v_bitop3_b32 v2, v199, v3, 4 bitop3:0x36
	v_lshlrev_b32_e32 v4, 7, v37
	v_lshlrev_b32_e32 v203, 4, v2
	v_bitop3_b32 v2, v199, v3, 6 bitop3:0x36
	s_ashr_i32 s92, s0, 4
	v_lshlrev_b32_e32 v204, 4, v2
	v_and_b32_e32 v2, 0xf80, v4
	s_waitcnt vmcnt(0)
	v_add_u32_e32 v205, 0, v2
	s_cmp_gt_i32 s72, -1
	s_mov_b32 s64, s20
	v_lshlrev_b32_e32 v210, 2, v199
	s_cselect_b64 s[66:67], -1, 0
	s_cmp_lt_i32 s72, 0
	v_add_u32_e32 v222, v205, v201
	v_add_u32_e32 v219, v205, v202
	v_add_u32_e32 v212, v205, v203
	v_add_u32_e32 v211, v205, v204
	s_nop 2
	v_readlane_b32 s8, v252, 11
	v_readlane_b32 s9, v252, 12
	s_mov_b64 s[14:15], s[18:19]
	s_waitcnt vmcnt(0) lgkmcnt(0)
	s_barrier
	s_cbranch_scc1 .LBB0_1077
	ds_read_b128 v[2:5], v222
	ds_read_b128 v[6:9], v222 offset:4096
	ds_read_b128 v[44:47], v219
	ds_read_b128 v[48:51], v219 offset:4096
	s_cmp_gt_i32 s92, 62
	s_waitcnt lgkmcnt(3)
	v_mfma_f32_32x32x16_bf16 v[18:33], v[2:5], v[162:165], 0
	s_waitcnt lgkmcnt(2)
	v_mfma_f32_32x32x16_bf16 v[2:17], v[6:9], v[162:165], 0
	s_waitcnt lgkmcnt(1)
	v_mfma_f32_32x32x16_bf16 v[18:33], v[44:47], v[166:169], v[18:33]
	s_waitcnt lgkmcnt(0)
	v_mfma_f32_32x32x16_bf16 v[2:17], v[48:51], v[166:169], v[2:17]
	ds_read_b128 v[44:47], v212
	ds_read_b128 v[48:51], v212 offset:4096
	s_waitcnt lgkmcnt(1)
	v_mfma_f32_32x32x16_bf16 v[18:33], v[44:47], v[170:173], v[18:33]
	s_waitcnt lgkmcnt(0)
	v_mfma_f32_32x32x16_bf16 v[2:17], v[48:51], v[170:173], v[2:17]
	ds_read_b128 v[44:47], v211
	ds_read_b128 v[48:51], v211 offset:4096
	s_waitcnt lgkmcnt(1)
	v_mfma_f32_32x32x16_bf16 v[18:33], v[44:47], v[174:177], v[18:33]
	s_waitcnt lgkmcnt(0)
	v_mfma_f32_32x32x16_bf16 v[2:17], v[48:51], v[174:177], v[2:17]
	s_cbranch_scc1 .LBB0_1076
	v_sub_u32_e32 v39, v40, v210
	v_cmp_gt_i32_e64 s[58:59], 26, v39
	v_cmp_gt_i32_e64 s[62:63], 27, v39
	v_cmp_gt_i32_e64 s[56:57], 25, v39
	s_and_b64 s[58:59], s[62:63], s[58:59]
	v_cmp_gt_i32_e64 s[54:55], 24, v39
	s_and_b64 s[56:57], s[58:59], s[56:57]
	v_cmp_gt_i32_e64 s[52:53], 19, v39
	s_and_b64 s[54:55], s[56:57], s[54:55]
	v_cmp_gt_i32_e64 s[50:51], 18, v39
	s_and_b64 s[52:53], s[54:55], s[52:53]
	v_cmp_gt_i32_e64 s[48:49], 17, v39
	s_and_b64 s[50:51], s[52:53], s[50:51]
	v_cmp_gt_i32_e64 s[46:47], 16, v39
	s_and_b64 s[48:49], s[50:51], s[48:49]
	v_cmp_gt_i32_e64 s[44:45], 11, v39
	s_and_b64 s[46:47], s[48:49], s[46:47]
	v_cmp_gt_i32_e64 s[42:43], 10, v39
	s_and_b64 s[44:45], s[46:47], s[44:45]
	v_cmp_gt_i32_e64 s[40:41], 9, v39
	s_and_b64 s[42:43], s[44:45], s[42:43]
	v_cmp_gt_i32_e64 s[38:39], 8, v39
	s_and_b64 s[40:41], s[42:43], s[40:41]
	v_cmp_gt_i32_e64 s[36:37], 3, v39
	s_and_b64 s[38:39], s[40:41], s[38:39]
	v_cmp_gt_i32_e64 s[34:35], 2, v39
	s_and_b64 s[36:37], s[38:39], s[36:37]
	v_cmp_gt_i32_e64 s[30:31], 1, v39
	s_and_b64 s[34:35], s[36:37], s[34:35]
	v_cmp_gt_i32_e64 s[28:29], 0, v39
	s_and_b64 s[30:31], s[34:35], s[30:31]
	s_and_b64 s[28:29], s[30:31], s[28:29]
	v_cmp_gt_i32_e64 s[60:61], 58, v39
	v_cndmask_b32_e64 v18, v18, v196, s[28:29]
	v_cmp_gt_i32_e64 s[28:29], 59, v39
	v_cmp_gt_i32_e64 s[26:27], 57, v39
	v_cmp_gt_i32_e64 s[24:25], 56, v39
	v_cndmask_b32_e64 v17, v17, v196, s[28:29]
	s_and_b64 s[28:29], s[28:29], s[60:61]
	s_and_b64 s[26:27], s[28:29], s[26:27]
	v_cmp_gt_i32_e64 s[22:23], 51, v39
	s_and_b64 s[24:25], s[26:27], s[24:25]
	v_cmp_gt_i32_e64 s[20:21], 50, v39
	s_and_b64 s[22:23], s[24:25], s[22:23]
	v_cmp_gt_i32_e64 s[18:19], 49, v39
	s_and_b64 s[20:21], s[22:23], s[20:21]
	v_cmp_gt_i32_e64 s[16:17], 48, v39
	s_and_b64 s[18:19], s[20:21], s[18:19]
	v_cmp_gt_i32_e64 s[14:15], 43, v39
	s_and_b64 s[16:17], s[18:19], s[16:17]
	v_cmp_gt_i32_e64 s[12:13], 42, v39
	s_and_b64 s[14:15], s[16:17], s[14:15]
	v_cmp_gt_i32_e64 s[8:9], 41, v39
	s_and_b64 s[12:13], s[14:15], s[12:13]
	v_cmp_gt_i32_e64 s[6:7], 40, v39
	s_and_b64 s[8:9], s[12:13], s[8:9]
	v_cmp_gt_i32_e64 s[4:5], 35, v39
	s_and_b64 s[6:7], s[8:9], s[6:7]
	v_cmp_gt_i32_e64 s[2:3], 34, v39
	s_and_b64 s[4:5], s[6:7], s[4:5]
	v_cmp_gt_i32_e64 s[0:1], 33, v39
	s_and_b64 s[2:3], s[4:5], s[2:3]
	v_cmp_gt_i32_e32 vcc, 32, v39
	s_and_b64 s[0:1], s[2:3], s[0:1]
	s_and_b64 vcc, s[0:1], vcc
	v_cndmask_b32_e64 v33, v33, v196, s[62:63]
	v_cndmask_b32_e64 v32, v32, v196, s[58:59]
	v_cndmask_b32_e64 v31, v31, v196, s[56:57]
	v_cndmask_b32_e64 v30, v30, v196, s[54:55]
	v_cndmask_b32_e64 v29, v29, v196, s[52:53]
	v_cndmask_b32_e64 v28, v28, v196, s[50:51]
	v_cndmask_b32_e64 v27, v27, v196, s[48:49]
	v_cndmask_b32_e64 v26, v26, v196, s[46:47]
	v_cndmask_b32_e64 v25, v25, v196, s[44:45]
	v_cndmask_b32_e64 v24, v24, v196, s[42:43]
	v_cndmask_b32_e64 v23, v23, v196, s[40:41]
	v_cndmask_b32_e64 v22, v22, v196, s[38:39]
	v_cndmask_b32_e64 v21, v21, v196, s[36:37]
	v_cndmask_b32_e64 v20, v20, v196, s[34:35]
	v_cndmask_b32_e64 v19, v19, v196, s[30:31]
	v_cndmask_b32_e64 v16, v16, v196, s[28:29]
	v_cndmask_b32_e64 v15, v15, v196, s[26:27]
	v_cndmask_b32_e64 v14, v14, v196, s[24:25]
	v_cndmask_b32_e64 v13, v13, v196, s[22:23]
	v_cndmask_b32_e64 v12, v12, v196, s[20:21]
	v_cndmask_b32_e64 v11, v11, v196, s[18:19]
	v_cndmask_b32_e64 v10, v10, v196, s[16:17]
	v_cndmask_b32_e64 v9, v9, v196, s[14:15]
	v_cndmask_b32_e64 v8, v8, v196, s[12:13]
	v_cndmask_b32_e64 v7, v7, v196, s[8:9]
	v_cndmask_b32_e64 v6, v6, v196, s[6:7]
	v_cndmask_b32_e64 v5, v5, v196, s[4:5]
	v_cndmask_b32_e64 v4, v4, v196, s[2:3]
	v_cndmask_b32_e64 v3, v3, v196, s[0:1]
	v_cndmask_b32_e32 v2, v2, v196, vcc

.LBB0_1147:
	v_lshlrev_b32_e32 v34, 12, v225
	v_add3_u32 v109, s77, v34, v38
	v_lshl_add_u32 v34, v226, 3, 0
	v_add_u32_e32 v34, 0x20000, v34
	v_pk_mul_f32 v[2:3], v[0:1], v[2:3] op_sel_hi:[0,1]
	s_waitcnt lgkmcnt(0)
	s_barrier
	ds_read_b64 v[102:103], v34
	v_cvt_pk_bf16_f32 v34, v2, v3
	v_pk_mul_f32 v[2:3], v[0:1], v[18:19] op_sel_hi:[0,1]
	v_cvt_pk_bf16_f32 v18, v2, v3
	v_pk_mul_f32 v[2:3], v[0:1], v[4:5] op_sel_hi:[0,1]
	v_cvt_pk_bf16_f32 v2, v2, v3
	ds_write2st64_b32 v109, v34, v2 offset1:1
	v_pk_mul_f32 v[2:3], v[0:1], v[20:21] op_sel_hi:[0,1]
	v_cvt_pk_bf16_f32 v2, v2, v3
	ds_write2st64_b32 v109, v18, v2 offset0:8 offset1:9
	v_pk_mul_f32 v[2:3], v[0:1], v[6:7] op_sel_hi:[0,1]
	v_cvt_pk_bf16_f32 v4, v2, v3
	v_pk_mul_f32 v[2:3], v[0:1], v[22:23] op_sel_hi:[0,1]
	v_cvt_pk_bf16_f32 v5, v2, v3
	v_pk_mul_f32 v[2:3], v[0:1], v[8:9] op_sel_hi:[0,1]
	v_cvt_pk_bf16_f32 v2, v2, v3
	ds_write2st64_b32 v109, v4, v2 offset0:2 offset1:3
	v_pk_mul_f32 v[2:3], v[0:1], v[24:25] op_sel_hi:[0,1]
	v_cvt_pk_bf16_f32 v2, v2, v3
	ds_write2st64_b32 v109, v5, v2 offset0:10 offset1:11
	v_pk_mul_f32 v[2:3], v[0:1], v[10:11] op_sel_hi:[0,1]
	v_cvt_pk_bf16_f32 v4, v2, v3
	v_pk_mul_f32 v[2:3], v[0:1], v[26:27] op_sel_hi:[0,1]
	v_cvt_pk_bf16_f32 v5, v2, v3
	v_pk_mul_f32 v[2:3], v[0:1], v[12:13] op_sel_hi:[0,1]
	v_cvt_pk_bf16_f32 v2, v2, v3
	ds_write2st64_b32 v109, v4, v2 offset0:4 offset1:5
	v_pk_mul_f32 v[2:3], v[0:1], v[28:29] op_sel_hi:[0,1]
	s_lshl_b32 s0, s64, 19
	v_readlane_b32 s4, v252, 7
	v_cvt_pk_bf16_f32 v2, v2, v3
	v_readlane_b32 s5, v252, 8
	s_add_u32 s0, s4, s0
	ds_write2st64_b32 v109, v5, v2 offset0:12 offset1:13
	v_pk_mul_f32 v[2:3], v[0:1], v[14:15] op_sel_hi:[0,1]
	s_addc_u32 s1, s5, 0
	v_cvt_pk_bf16_f32 v4, v2, v3
	v_pk_mul_f32 v[2:3], v[0:1], v[30:31] op_sel_hi:[0,1]
	v_lshl_add_u64 v[98:99], v[186:187], 1, s[0:1]
	v_lshl_add_u64 v[100:101], v[188:189], 1, s[0:1]
	s_mov_b64 s[0:1], 0x1800000
	v_cvt_pk_bf16_f32 v5, v2, v3
	v_pk_mul_f32 v[2:3], v[0:1], v[16:17] op_sel_hi:[0,1]
	v_lshl_add_u64 v[106:107], v[100:101], 0, s[0:1]
	s_min_i32 s0, s68, 0
	v_cvt_pk_bf16_f32 v2, v2, v3
	s_mov_b64 s[2:3], 0x1000000
	s_ashr_i32 s1, s0, 31
	ds_write2st64_b32 v109, v4, v2 offset0:6 offset1:7
	v_pk_mul_f32 v[2:3], v[0:1], v[32:33] op_sel_hi:[0,1]
	v_lshl_add_u64 v[104:105], v[98:99], 0, s[2:3]
	s_lshl_b64 s[0:1], s[0:1], 13
	v_readfirstlane_b32 s2, v200
	v_cvt_pk_bf16_f32 v0, v2, v3
	v_lshl_add_u64 v[2:3], v[104:105], 0, s[0:1]
	s_mov_b32 m0, s2
	ds_write2st64_b32 v109, v5, v0 offset0:14 offset1:15
	global_load_lds_dwordx4 v[2:3], off
	v_lshl_add_u64 v[2:3], v[106:107], 0, s[0:1]
	v_readfirstlane_b32 s0, v213
	s_mov_b32 m0, s0
	s_min_i32 s0, s68, 1
	s_ashr_i32 s1, s0, 31
	s_lshl_b64 s[0:1], s[0:1], 13
	v_readfirstlane_b32 s2, v214
	global_load_lds_dwordx4 v[2:3], off
	v_lshl_add_u64 v[2:3], v[104:105], 0, s[0:1]
	s_mov_b32 m0, s2
	v_readfirstlane_b32 s2, v216
	global_load_lds_dwordx4 v[2:3], off
	v_lshl_add_u64 v[2:3], v[106:107], 0, s[0:1]
	v_readfirstlane_b32 s0, v215
	s_mov_b32 m0, s0
	s_min_i32 s0, s68, 2
	s_ashr_i32 s1, s0, 31
	s_lshl_b64 s[0:1], s[0:1], 13
	global_load_lds_dwordx4 v[2:3], off
	v_lshl_add_u64 v[2:3], v[104:105], 0, s[0:1]
	s_mov_b32 m0, s2
	v_readfirstlane_b32 s2, v218
	global_load_lds_dwordx4 v[2:3], off
	v_lshl_add_u64 v[2:3], v[106:107], 0, s[0:1]
	v_readfirstlane_b32 s0, v217
	s_mov_b32 m0, s0
	s_min_i32 s0, s68, 3
	s_ashr_i32 s1, s0, 31
	s_lshl_b64 s[0:1], s[0:1], 13
	global_load_lds_dwordx4 v[2:3], off
	v_lshl_add_u64 v[2:3], v[104:105], 0, s[0:1]
	s_mov_b32 m0, s2
	v_add_u32_e32 v113, s76, v224
	global_load_lds_dwordx4 v[2:3], off
	v_lshl_add_u64 v[2:3], v[106:107], 0, s[0:1]
	v_readfirstlane_b32 s0, v221
	s_mov_b32 m0, s0
	s_min_i32 s0, s68, 4
	s_ashr_i32 s1, s0, 31
	s_lshl_b64 s[0:1], s[0:1], 13
	v_readfirstlane_b32 s2, v113
	global_load_lds_dwordx4 v[2:3], off
	v_lshl_add_u64 v[2:3], v[104:105], 0, s[0:1]
	s_mov_b32 m0, s2
	v_add_u32_e32 v114, s78, v224
	global_load_lds_dwordx4 v[2:3], off
	v_lshl_add_u64 v[2:3], v[106:107], 0, s[0:1]
	v_readfirstlane_b32 s0, v114
	s_mov_b32 m0, s0
	v_lshlrev_b32_e32 v0, 8, v199
	global_load_lds_dwordx4 v[2:3], off
	s_waitcnt vmcnt(8)
	s_barrier
	ds_read_b128 v[2:5], v222
	ds_read_b128 v[6:9], v222 offset:4096
	s_waitcnt lgkmcnt(0)
	v_mfma_f32_32x32x16_bf16 v[34:49], v[2:5], v[162:165], 0
	s_mov_b32 s42, 0
	s_cmp_lt_i32 s74, 64
	s_nop 4
	v_mfma_f32_32x32x16_bf16 v[50:65], v[6:9], v[162:165], 0
	ds_read_b128 v[2:5], v219
	ds_read_b128 v[6:9], v219 offset:4096
	s_nop 0
	v_readlane_b32 s12, v252, 15
	v_readlane_b32 s13, v252, 16
	s_nop 1
	v_readlane_b32 s16, v252, 19
	s_waitcnt lgkmcnt(0)
	v_mfma_f32_32x32x16_bf16 v[34:49], v[2:5], v[166:169], v[34:49]
	v_readlane_b32 s17, v252, 20
	v_readlane_b32 s18, v252, 21
	v_readlane_b32 s19, v252, 22
	v_mfma_f32_32x32x16_bf16 v[50:65], v[6:9], v[166:169], v[50:65]
	ds_read_b128 v[2:5], v212
	ds_read_b128 v[6:9], v212 offset:4096
	s_waitcnt lgkmcnt(0)
	v_mfma_f32_32x32x16_bf16 v[34:49], v[2:5], v[170:173], v[34:49]
	v_mfma_f32_32x32x16_bf16 v[50:65], v[6:9], v[170:173], v[50:65]
	ds_read_b128 v[2:5], v211
	ds_read_b128 v[6:9], v211 offset:4096
	s_waitcnt lgkmcnt(0)
	v_mfma_f32_32x32x16_bf16 v[34:49], v[2:5], v[174:177], v[34:49]
	v_and_b32_e32 v2, 0xc0, v224
	v_add3_u32 v0, 0, v0, v2
	v_add3_u32 v112, v0, v229, v228
	v_mfma_f32_32x32x16_bf16 v[50:65], v[6:9], v[174:177], v[50:65]
	s_cbranch_scc0 .LBB0_1176
	v_mov_b32_e32 v2, v1
	v_mov_b32_e32 v3, v1
	v_mov_b32_e32 v4, v1
	v_mov_b32_e32 v5, v1
	v_mov_b32_e32 v6, v1
	v_mov_b32_e32 v7, v1
	v_mov_b32_e32 v8, v1
	v_mov_b32_e32 v9, v1
	v_mov_b32_e32 v10, v1
	v_mov_b32_e32 v11, v1
	v_mov_b32_e32 v12, v1
	v_mov_b32_e32 v13, v1
	v_mov_b32_e32 v14, v1
	v_mov_b32_e32 v15, v1
	v_mov_b32_e32 v16, v1
	v_mov_b32_e32 v17, v1
	v_mov_b32_e32 v18, v1
	v_mov_b32_e32 v19, v1
	v_mov_b32_e32 v20, v1
	v_mov_b32_e32 v21, v1
	v_mov_b32_e32 v22, v1
	v_mov_b32_e32 v23, v1
	v_mov_b32_e32 v24, v1
	v_mov_b32_e32 v25, v1
	v_mov_b32_e32 v26, v1
	v_mov_b32_e32 v27, v1
	v_mov_b32_e32 v28, v1
	v_mov_b32_e32 v29, v1
	v_mov_b32_e32 v30, v1
	v_mov_b32_e32 v31, v1
	v_mov_b32_e32 v0, v1
	v_mov_b64_e32 v[32:33], v[30:31]
	v_cmp_gt_i32_e64 s[0:1], 0, v184
	s_mov_b32 s43, 5
	s_mov_b64 s[38:39], -1
	v_mov_b32_e32 v115, 0
	v_mov_b32_e32 v116, 0xf149f2ca
	s_movk_i32 s44, 0x7f
	v_mov_b64_e32 v[30:31], v[28:29]
	v_mov_b64_e32 v[28:29], v[26:27]
	v_mov_b64_e32 v[26:27], v[24:25]
	v_mov_b64_e32 v[24:25], v[22:23]
	v_mov_b64_e32 v[22:23], v[20:21]
	v_mov_b64_e32 v[20:21], v[18:19]
	v_mov_b64_e32 v[18:19], v[16:17]
	v_mov_b64_e32 v[16:17], v[14:15]
	v_mov_b64_e32 v[14:15], v[12:13]
	v_mov_b64_e32 v[12:13], v[10:11]
	v_mov_b64_e32 v[10:11], v[8:9]
	v_mov_b64_e32 v[8:9], v[6:7]
	v_mov_b64_e32 v[6:7], v[4:5]
	v_mov_b64_e32 v[4:5], v[2:3]
	v_mov_b64_e32 v[2:3], v[0:1]
	s_mov_b32 s45, 0
	s_waitcnt lgkmcnt(0)
	v_mov_b32_e32 v238, v102
	v_mov_b32_e32 v239, v103
	s_nop 1
	v_or_b32_dpp v238, v238, v238 quad_perm:[1,0,3,2] row_mask:0xf bank_mask:0xf
	v_or_b32_dpp v239, v239, v239 quad_perm:[1,0,3,2] row_mask:0xf bank_mask:0xf
	s_nop 1
	v_or_b32_dpp v238, v238, v238 quad_perm:[2,3,0,1] row_mask:0xf bank_mask:0xf
	v_or_b32_dpp v239, v239, v239 quad_perm:[2,3,0,1] row_mask:0xf bank_mask:0xf
	s_nop 1
	v_or_b32_dpp v238, v238, v238 row_half_mirror row_mask:0xf bank_mask:0xf
	v_or_b32_dpp v239, v239, v239 row_half_mirror row_mask:0xf bank_mask:0xf
	s_nop 1
	v_or_b32_dpp v238, v238, v238 row_mirror row_mask:0xf bank_mask:0xf
	v_or_b32_dpp v239, v239, v239 row_mirror row_mask:0xf bank_mask:0xf
	s_nop 1
	v_readlane_b32 s100, v238, 0
	v_readlane_b32 s2, v238, 16
	v_readlane_b32 s3, v238, 32
	v_readlane_b32 s101, v238, 48
	s_or_b32 s100, s100, s2
	s_or_b32 s3, s3, s101
	s_or_b32 s100, s100, s3
	v_readlane_b32 s101, v239, 0
	v_readlane_b32 s2, v239, 16
	v_readlane_b32 s3, v239, 32
	s_or_b32 s101, s101, s2
	v_readlane_b32 s2, v239, 48
	s_or_b32 s101, s101, s3
	s_or_b32 s101, s101, s2
	s_branch .LBB0_1150

.LBB0_1150:
	s_add_i32 s2, s42, 5
	s_min_i32 s72, s2, s68
	s_lshl_b32 s98, s43, 14
	s_add_i32 s98, s98, s99
	s_lshl_b64 s[2:3], s[72:73], 13
	s_mov_b32 s4, s98
	v_lshl_add_u64 v[110:111], v[104:105], 0, s[2:3]
	s_mov_b32 m0, s4
	s_waitcnt vmcnt(6)
	s_barrier
	global_load_lds_dwordx4 v[110:111], off
	v_lshl_add_u64 v[110:111], v[106:107], 0, s[2:3]
	s_add_i32 s2, s98, 0x2000
	s_mov_b32 m0, s2
	s_add_i32 s2, s45, 1
	global_load_lds_dwordx4 v[110:111], off
	s_cmp_lg_u32 s45, 5
	s_cselect_b32 s46, s2, 0
	s_cmp_lt_i32 s42, s68
	s_cselect_b64 s[40:41], -1, 0
	s_cmp_ge_i32 s42, s68
	s_mov_b64 s[10:11], 0
	s_cbranch_scc1 .LBB0_1153
	s_add_i32 s2, s42, 1
	s_bitcmp1_b64 s[100:101], s2
	s_cbranch_scc0 .LBB0_1153
	v_lshl_add_u32 v0, s46, 14, v205
	v_add_u32_e32 v70, v0, v201
	ds_read_b128 v[66:69], v70
	ds_read_b128 v[82:85], v70 offset:4096
	v_add_u32_e32 v108, v0, v202
	ds_read_b128 v[118:121], v108
	ds_read_b128 v[122:125], v108 offset:4096
	v_add_u32_e32 v108, v0, v203
	ds_read_b128 v[126:129], v108
	ds_read_b128 v[130:133], v108 offset:4096
	v_add_u32_e32 v0, v0, v204
	ds_read_b128 v[134:137], v0
	ds_read_b128 v[138:141], v0 offset:4096
	s_mov_b64 s[10:11], -1
	s_waitcnt lgkmcnt(6)
	v_mfma_f32_32x32x16_bf16 v[66:81], v[66:69], v[162:165], 0
	v_mfma_f32_32x32x16_bf16 v[82:97], v[82:85], v[162:165], 0
	s_waitcnt lgkmcnt(4)
	v_mfma_f32_32x32x16_bf16 v[66:81], v[118:121], v[166:169], v[66:81]
	v_mfma_f32_32x32x16_bf16 v[82:97], v[122:125], v[166:169], v[82:97]
	s_waitcnt lgkmcnt(2)
	v_mfma_f32_32x32x16_bf16 v[66:81], v[126:129], v[170:173], v[66:81]
	v_mfma_f32_32x32x16_bf16 v[82:97], v[130:133], v[170:173], v[82:97]
	s_waitcnt lgkmcnt(0)
	v_mfma_f32_32x32x16_bf16 v[66:81], v[134:137], v[174:177], v[66:81]
	v_mfma_f32_32x32x16_bf16 v[82:97], v[138:141], v[174:177], v[82:97]

.LBB0_1162:
	s_add_i32 s2, s43, 1
	s_cmp_lg_u32 s43, 5
	s_cselect_b32 s43, s2, 0
	s_andn2_b64 vcc, exec, s[40:41]
	s_cbranch_vccnz .LBB0_1149
	s_add_i32 s2, s42, 6
	s_min_i32 s72, s2, s68
	s_lshl_b32 s98, s43, 14
	s_add_i32 s98, s98, s99
	s_lshl_b64 s[2:3], s[72:73], 13
	s_mov_b32 s4, s98
	v_lshl_add_u64 v[110:111], v[104:105], 0, s[2:3]
	s_mov_b32 m0, s4
	s_waitcnt vmcnt(6)
	s_barrier
	global_load_lds_dwordx4 v[110:111], off
	v_lshl_add_u64 v[110:111], v[106:107], 0, s[2:3]
	s_add_i32 s2, s98, 0x2000
	s_mov_b32 m0, s2
	s_add_i32 s40, s42, 1
	global_load_lds_dwordx4 v[110:111], off
	s_add_i32 s2, s46, 1
	s_cmp_lg_u32 s46, 5
	s_cselect_b32 s45, s2, 0
	s_cmp_ge_i32 s40, s68
	s_mov_b64 s[38:39], 0
	s_cbranch_scc1 .LBB0_1166
	s_add_i32 s2, s42, 2
	s_bitcmp1_b64 s[100:101], s2
	s_cbranch_scc0 .LBB0_1166
	v_lshl_add_u32 v0, s45, 14, v205
	v_add_u32_e32 v38, v0, v201
	ds_read_b128 v[34:37], v38
	ds_read_b128 v[50:53], v38 offset:4096
	v_add_u32_e32 v108, v0, v202
	ds_read_b128 v[118:121], v108
	ds_read_b128 v[122:125], v108 offset:4096
	v_add_u32_e32 v108, v0, v203
	ds_read_b128 v[126:129], v108
	ds_read_b128 v[130:133], v108 offset:4096
	v_add_u32_e32 v0, v0, v204
	ds_read_b128 v[134:137], v0
	ds_read_b128 v[138:141], v0 offset:4096
	s_mov_b64 s[38:39], -1
	s_waitcnt lgkmcnt(6)
	v_mfma_f32_32x32x16_bf16 v[34:49], v[34:37], v[162:165], 0
	v_mfma_f32_32x32x16_bf16 v[50:65], v[50:53], v[162:165], 0
	s_waitcnt lgkmcnt(4)
	v_mfma_f32_32x32x16_bf16 v[34:49], v[118:121], v[166:169], v[34:49]
	v_mfma_f32_32x32x16_bf16 v[50:65], v[122:125], v[166:169], v[50:65]
	s_waitcnt lgkmcnt(2)
	v_mfma_f32_32x32x16_bf16 v[34:49], v[126:129], v[170:173], v[34:49]
	v_mfma_f32_32x32x16_bf16 v[50:65], v[130:133], v[170:173], v[50:65]
	s_waitcnt lgkmcnt(0)
	v_mfma_f32_32x32x16_bf16 v[34:49], v[134:137], v[174:177], v[34:49]
	v_mfma_f32_32x32x16_bf16 v[50:65], v[138:141], v[174:177], v[50:65]

.LBB0_1181:
	s_add_i32 s0, s40, 5
	s_min_i32 s0, s0, s68
	s_ashr_i32 s1, s0, 31
	s_lshl_b32 s98, s43, 14
	s_add_i32 s98, s98, s99
	s_lshl_b64 s[0:1], s[0:1], 13
	s_mov_b32 s2, s98
	v_lshl_add_u64 v[104:105], v[98:99], 0, s[0:1]
	s_mov_b32 m0, s2
	s_waitcnt vmcnt(6)
	s_barrier
	global_load_lds_dwordx4 v[104:105], off
	v_lshl_add_u64 v[104:105], v[100:101], 0, s[0:1]
	s_add_i32 s0, s98, 0x2000
	s_mov_b32 m0, s0
	s_add_i32 s0, s44, 1
	global_load_lds_dwordx4 v[104:105], off
	s_cmp_lg_u32 s44, 5
	s_cselect_b32 s45, s0, 0
	s_cmp_lt_i32 s40, s68
	s_cselect_b64 s[10:11], -1, 0
	s_cmp_ge_i32 s40, s68
	s_cbranch_scc1 .LBB0_1183
	v_lshl_add_u32 v0, s45, 14, v205
	v_add_u32_e32 v70, v0, v201
	ds_read_b128 v[66:69], v70
	ds_read_b128 v[82:85], v70 offset:4096
	v_add_u32_e32 v102, v0, v202
	ds_read_b128 v[114:117], v102
	ds_read_b128 v[118:121], v102 offset:4096
	v_add_u32_e32 v102, v0, v203
	ds_read_b128 v[122:125], v102
	ds_read_b128 v[126:129], v102 offset:4096
	v_add_u32_e32 v0, v0, v204
	ds_read_b128 v[130:133], v0
	ds_read_b128 v[134:137], v0 offset:4096
	s_waitcnt lgkmcnt(6)
	v_mfma_f32_32x32x16_bf16 v[66:81], v[66:69], v[162:165], 0
	v_mfma_f32_32x32x16_bf16 v[82:97], v[82:85], v[162:165], 0
	s_waitcnt lgkmcnt(4)
	v_mfma_f32_32x32x16_bf16 v[66:81], v[114:117], v[166:169], v[66:81]
	v_mfma_f32_32x32x16_bf16 v[82:97], v[118:121], v[166:169], v[82:97]
	s_waitcnt lgkmcnt(2)
	v_mfma_f32_32x32x16_bf16 v[66:81], v[122:125], v[170:173], v[66:81]
	v_mfma_f32_32x32x16_bf16 v[82:97], v[126:129], v[170:173], v[82:97]
	s_waitcnt lgkmcnt(0)
	v_mfma_f32_32x32x16_bf16 v[66:81], v[130:133], v[174:177], v[66:81]
	v_mfma_f32_32x32x16_bf16 v[82:97], v[134:137], v[174:177], v[82:97]

.LBB0_1192:
	s_add_i32 s0, s43, 1
	s_cmp_lg_u32 s43, 5
	s_cselect_b32 s43, s0, 0
	s_andn2_b64 vcc, exec, s[10:11]
	s_cbranch_vccnz .LBB0_1179
	s_add_i32 s0, s40, 6
	s_min_i32 s0, s0, s68
	s_ashr_i32 s1, s0, 31
	s_lshl_b32 s98, s43, 14
	s_add_i32 s98, s98, s99
	s_lshl_b64 s[0:1], s[0:1], 13
	s_mov_b32 s2, s98
	v_lshl_add_u64 v[104:105], v[98:99], 0, s[0:1]
	s_mov_b32 m0, s2
	s_waitcnt vmcnt(6)
	s_barrier
	global_load_lds_dwordx4 v[104:105], off
	v_lshl_add_u64 v[104:105], v[100:101], 0, s[0:1]
	s_add_i32 s0, s98, 0x2000
	s_mov_b32 m0, s0
	s_add_i32 s0, s40, 1
	global_load_lds_dwordx4 v[104:105], off
	s_add_i32 s1, s45, 1
	s_cmp_lg_u32 s45, 5
	s_cselect_b32 s44, s1, 0
	s_cmp_lt_i32 s0, s68
	s_cselect_b64 s[36:37], -1, 0
	s_cmp_ge_i32 s0, s68
	s_cbranch_scc1 .LBB0_1195
	v_lshl_add_u32 v0, s44, 14, v205
	v_add_u32_e32 v38, v0, v201
	ds_read_b128 v[34:37], v38
	ds_read_b128 v[50:53], v38 offset:4096
	v_add_u32_e32 v102, v0, v202
	ds_read_b128 v[114:117], v102
	ds_read_b128 v[118:121], v102 offset:4096
	v_add_u32_e32 v102, v0, v203
	ds_read_b128 v[122:125], v102
	ds_read_b128 v[126:129], v102 offset:4096
	v_add_u32_e32 v0, v0, v204
	ds_read_b128 v[130:133], v0
	ds_read_b128 v[134:137], v0 offset:4096
	s_waitcnt lgkmcnt(6)
	v_mfma_f32_32x32x16_bf16 v[34:49], v[34:37], v[162:165], 0
	v_mfma_f32_32x32x16_bf16 v[50:65], v[50:53], v[162:165], 0
	s_waitcnt lgkmcnt(4)
	v_mfma_f32_32x32x16_bf16 v[34:49], v[114:117], v[166:169], v[34:49]
	v_mfma_f32_32x32x16_bf16 v[50:65], v[118:121], v[166:169], v[50:65]
	s_waitcnt lgkmcnt(2)
	v_mfma_f32_32x32x16_bf16 v[34:49], v[122:125], v[170:173], v[34:49]
	v_mfma_f32_32x32x16_bf16 v[50:65], v[126:129], v[170:173], v[50:65]
	s_waitcnt lgkmcnt(0)
	v_mfma_f32_32x32x16_bf16 v[34:49], v[130:133], v[174:177], v[34:49]
	v_mfma_f32_32x32x16_bf16 v[50:65], v[134:137], v[174:177], v[50:65]
